# sample-mLSTM unit: all 32 state-row loads requested together (23 had been issued only after the gate math), copied at the original sites
# speedup vs baseline: 1.0014x; 1.0014x over previous
; DI void smlstm_unit(const Args& a, LAS unsigned char* lds, int s, int h) {
;     ...
;     const float* gr = (const float*)(ws + WS_GA) + row * 32; const float ip = gr[24 + h], fp = gr[28 + h], m0 = INF(a, I_SM)[sh];
;     const float lf = fminf(fp, 0.f) - log1pf(__expf(-fabsf(fp))), ain = lf + m0, mt = fmaxf(ain, ip), w_in = __expf(ain - mt), wi = __expf(ip - mt);
;     ...
;       for (int i = 0; i < 32; ++i) c0v[i] = C0[(size_t)(part * 32 + i) * 128 + dv];
.LBB0_2131:
	s_or_b64 exec, exec, s[20:21]
	s_ashr_i32 s9, s8, 31
	s_lshl_b64 s[20:21], s[0:1], 7
	s_add_u32 s20, s23, s20
	s_addc_u32 s21, s24, s21
	s_lshl_b32 s42, s41, 2
	v_mov_b32_e32 v2, s42
	global_load_dword v6, v2, s[20:21] offset:112
	global_load_dword v8, v2, s[20:21] offset:96
	s_lshl_b64 s[20:21], s[8:9], 2
	v_readlane_b32 s44, v253, 36
	v_readlane_b32 s45, v253, 37
	s_add_u32 s20, s44, s20
	s_addc_u32 s21, s45, s21
	global_load_dword v9, v133, s[20:21]
	s_lshl_b64 s[42:43], s[8:9], 16
	v_lshl_add_u64 v[2:3], v[134:135], 0, s[42:43]
	s_waitcnt lgkmcnt(1)
	v_add_co_u32_e32 v4, vcc, s38, v2
	s_waitcnt lgkmcnt(0)
	s_nop 0
	v_addc_co_u32_e32 v5, vcc, 0, v3, vcc
	s_barrier
	global_load_dword v19, v[2:3], off
	global_load_dword v32, v[2:3], off offset:512
	global_load_dword v33, v[2:3], off offset:1024
	global_load_dword v34, v[2:3], off offset:1536
	global_load_dword v44, v[2:3], off offset:2048
	global_load_dword v45, v[2:3], off offset:2560
	global_load_dword v46, v[2:3], off offset:3072
	global_load_dword v47, v[2:3], off offset:3584
	global_load_dword v48, v[4:5], off offset:-4096
	v_add_co_u32_e32 v186, vcc, s37, v2
	s_nop 1
	v_addc_co_u32_e32 v187, vcc, 0, v3, vcc
	v_add_co_u32_e32 v188, vcc, s22, v2
	s_nop 1
	v_addc_co_u32_e32 v189, vcc, 0, v3, vcc
	global_load_dword v190, v[186:187], off offset:512
	global_load_dword v191, v[186:187], off offset:1024
	global_load_dword v192, v[186:187], off offset:1536
	global_load_dword v193, v[4:5], off
	global_load_dword v194, v[4:5], off offset:512
	global_load_dword v195, v[4:5], off offset:1024
	global_load_dword v196, v[4:5], off offset:1536
	global_load_dword v197, v[4:5], off offset:2048
	global_load_dword v198, v[4:5], off offset:2560
	global_load_dword v199, v[4:5], off offset:3072
	global_load_dword v200, v[4:5], off offset:3584
	global_load_dword v201, v[186:187], off offset:2048
	global_load_dword v202, v[186:187], off offset:2560
	global_load_dword v203, v[186:187], off offset:3072
	global_load_dword v204, v[186:187], off offset:3584
	global_load_dword v205, v[188:189], off
	global_load_dword v206, v[188:189], off offset:512
	global_load_dword v207, v[188:189], off offset:1024
	global_load_dword v208, v[188:189], off offset:1536
	global_load_dword v209, v[188:189], off offset:2048
	global_load_dword v210, v[188:189], off offset:2560
	global_load_dword v211, v[188:189], off offset:3072
	global_load_dword v212, v[188:189], off offset:3584
	s_add_u32 s20, s25, s42
	s_addc_u32 s21, s26, s43
	v_readlane_b32 s46, v253, 38
	v_readlane_b32 s47, v253, 39
	v_readlane_b32 s48, v253, 40
	v_readlane_b32 s49, v253, 41
	v_readlane_b32 s50, v253, 42
	v_readlane_b32 s51, v253, 43
	v_readlane_b32 s52, v253, 44
	v_readlane_b32 s53, v253, 45
	v_readlane_b32 s54, v253, 46
	v_readlane_b32 s55, v253, 47
	v_readlane_b32 s56, v253, 48
	v_readlane_b32 s57, v253, 49
	v_readlane_b32 s58, v253, 50
	v_readlane_b32 s59, v253, 51
	s_waitcnt vmcnt(11)
	v_mul_f32_e64 v7, |v6|, s31
	v_exp_f32_e32 v10, v7
	v_max_f32_e32 v6, v6, v6
	v_min_f32_e32 v12, 0, v6
	s_waitcnt vmcnt(10)
	v_max_f32_e32 v11, v8, v8
	v_add_f32_e32 v13, 1.0, v10
	v_add_f32_e32 v14, -1.0, v13
	v_frexp_mant_f32_e32 v15, v13
	v_cvt_f64_f32_e32 v[6:7], v13
	v_sub_f32_e32 v16, v14, v13
	v_frexp_exp_i32_f64_e32 v6, v[6:7]
	v_cmp_gt_f32_e32 vcc, s33, v15
	v_sub_f32_e32 v14, v10, v14
	v_add_f32_e32 v7, 1.0, v16
	v_subbrev_co_u32_e32 v6, vcc, 0, v6, vcc
	v_add_f32_e32 v7, v14, v7
	v_sub_u32_e32 v14, 0, v6
	v_cvt_f32_i32_e32 v6, v6
	v_ldexp_f32 v13, v13, v14
	v_ldexp_f32 v7, v7, v14
	v_add_f32_e32 v14, -1.0, v13
	v_add_f32_e32 v15, 1.0, v13
	v_add_f32_e32 v16, 1.0, v14
	v_add_f32_e32 v17, -1.0, v15
	v_sub_f32_e32 v16, v13, v16
	v_sub_f32_e32 v13, v13, v17
	v_mul_f32_e32 v17, 0x3f317218, v6
	v_add_f32_e32 v16, v7, v16
	v_add_f32_e32 v7, v7, v13
	v_fma_f32 v13, v6, s34, -v17
	v_add_f32_e32 v18, v14, v16
	v_add_f32_e32 v20, v15, v7
	v_fmac_f32_e32 v13, 0xb102e308, v6
	v_sub_f32_e32 v6, v18, v14
	v_sub_f32_e32 v14, v20, v15
	v_rcp_f32_e32 v15, v20
	v_add_f32_e32 v21, v17, v13
	v_sub_f32_e32 v7, v7, v14
	v_sub_f32_e32 v14, v21, v17
	v_sub_f32_e32 v13, v13, v14
	v_mul_f32_e32 v14, v18, v15
	v_sub_f32_e32 v6, v16, v6
	v_mul_f32_e32 v16, v20, v14
	v_fma_f32 v17, v14, v20, -v16
	v_fmac_f32_e32 v17, v14, v7
	v_add_f32_e32 v22, v16, v17
	v_sub_f32_e32 v23, v18, v22
	v_sub_f32_e32 v16, v22, v16
	v_sub_f32_e32 v18, v18, v23
	v_sub_f32_e32 v16, v16, v17
	v_sub_f32_e32 v17, v18, v22
	v_add_f32_e32 v6, v6, v17
	v_add_f32_e32 v6, v16, v6
	v_add_f32_e32 v16, v23, v6
	v_mul_f32_e32 v17, v15, v16
	v_sub_f32_e32 v18, v23, v16
	v_mul_f32_e32 v22, v20, v17
	v_add_f32_e32 v6, v6, v18
	v_add_f32_e32 v18, v14, v17
	v_fma_f32 v20, v17, v20, -v22
	v_sub_f32_e32 v14, v18, v14
	v_fmac_f32_e32 v20, v17, v7
	v_sub_f32_e32 v7, v17, v14
	v_add_f32_e32 v14, v22, v20
	v_sub_f32_e32 v17, v14, v22
	v_sub_f32_e32 v22, v16, v14
	v_sub_f32_e32 v16, v16, v22
	v_sub_f32_e32 v14, v16, v14
	v_sub_f32_e32 v17, v17, v20
	v_add_f32_e32 v6, v6, v14
	v_add_f32_e32 v6, v17, v6
	v_add_f32_e32 v6, v22, v6
	v_mul_f32_e32 v6, v15, v6
	v_add_f32_e32 v6, v7, v6
	v_add_f32_e32 v7, v18, v6
	v_mul_f32_e32 v14, v7, v7
	v_fmamk_f32 v17, v14, 0x3e9b6dac, v138
	v_sub_f32_e32 v15, v7, v18
	v_ldexp_f32 v16, v7, 1
	v_mul_f32_e32 v7, v7, v14
	v_fmaak_f32 v14, v14, v17, 0x3f2aaada
	v_mul_f32_e32 v7, v7, v14
	v_add_f32_e32 v14, v16, v7
	v_sub_f32_e32 v6, v6, v15
	v_sub_f32_e32 v15, v14, v16
	v_ldexp_f32 v6, v6, 1
	v_sub_f32_e32 v7, v7, v15
	v_add_f32_e32 v6, v6, v7
	v_add_f32_e32 v7, v14, v6
	v_sub_f32_e32 v14, v7, v14
	v_add_f32_e32 v15, v21, v7
	v_sub_f32_e32 v6, v6, v14
	v_sub_f32_e32 v14, v15, v21
	v_sub_f32_e32 v16, v15, v14
	v_sub_f32_e32 v7, v7, v14
	v_add_f32_e32 v14, v13, v6
	v_sub_f32_e32 v16, v21, v16
	v_sub_f32_e32 v17, v14, v13
	v_add_f32_e32 v7, v7, v16
	v_sub_f32_e32 v16, v14, v17
	v_sub_f32_e32 v6, v6, v17
	v_sub_f32_e32 v13, v13, v16
	v_add_f32_e32 v7, v14, v7
	v_add_f32_e32 v6, v6, v13
	v_add_f32_e32 v13, v15, v7
	v_sub_f32_e32 v14, v13, v15
	v_sub_f32_e32 v7, v7, v14
	v_add_f32_e32 v6, v6, v7
	v_add_f32_e32 v6, v13, v6
	v_cmp_neq_f32_e32 vcc, s35, v10
	s_nop 1
	v_cndmask_b32_e32 v6, v181, v6, vcc
	v_cmp_ngt_f32_e32 vcc, -1.0, v10
	s_nop 1
	v_cndmask_b32_e32 v6, v182, v6, vcc
	v_cmp_neq_f32_e32 vcc, -1.0, v10
	s_nop 1
	v_cndmask_b32_e32 v6, v183, v6, vcc
	v_cmp_lt_f32_e64 vcc, |v10|, s36
	s_nop 1
	v_cndmask_b32_e32 v6, v6, v10, vcc
	v_sub_f32_e32 v6, v12, v6
	s_waitcnt vmcnt(9)
; DI void smlstm_unit(const Args& a, LAS unsigned char* lds, int s, int h) {
;     ...
;     const float lf = fminf(fp, 0.f) - log1pf(__expf(-fabsf(fp))), ain = lf + m0, mt = fmaxf(ain, ip), w_in = __expf(ain - mt), wi = __expf(ip - mt);
;     __syncthreads();
;     float num = 0.f; float* Co = a.out + O_CS + (size_t)sh * 16384; const float vv = VF[dv];
;     { float c0v[32];
; #pragma unroll
;       for (int i = 0; i < 32; ++i) c0v[i] = C0[(size_t)(part * 32 + i) * 128 + dv];
; #pragma unroll
;       for (int i = 0; i < 32; ++i) { const int dk = part * 32 + i; num += QF[dk] * c0v[i]; Co[(size_t)dk * 128 + dv] = w_in * c0v[i] + wi * KF[dk] * vv; } }
	v_add_f32_e32 v6, v9, v6
	v_max_f32_e32 v18, v6, v11
	v_sub_f32_e32 v6, v6, v18
	v_sub_f32_e32 v7, v8, v18
	v_mul_f32_e32 v28, 0x3fb8aa3b, v6
	v_add_co_u32_e32 v6, vcc, s37, v2
	v_mul_f32_e32 v29, 0x3fb8aa3b, v7
	s_nop 0
	v_addc_co_u32_e32 v7, vcc, 0, v3, vcc
	s_waitcnt vmcnt(0)
	v_mov_b32_e32 v49, v190
	v_mov_b32_e32 v50, v191
	v_mov_b32_e32 v51, v192
	v_mov_b32_e32 v52, v193
	v_mov_b32_e32 v53, v194
	v_mov_b32_e32 v54, v195
	v_mov_b32_e32 v55, v196
	v_mov_b32_e32 v16, v197
	v_mov_b32_e32 v17, v198
	v_mov_b32_e32 v14, v199
	v_mov_b32_e32 v15, v200
	v_add_co_u32_e32 v4, vcc, s22, v2
	s_nop 1
	v_addc_co_u32_e32 v5, vcc, 0, v3, vcc
	v_mov_b32_e32 v2, v201
	v_mov_b32_e32 v56, v202
	v_mov_b32_e32 v57, v203
	v_mov_b32_e32 v58, v204
	v_mov_b32_e32 v12, v205
	ds_read_b32 v3, v131 offset:1024
	ds_read_b128 v[20:23], v136
	v_mov_b32_e32 v13, v206
	v_mov_b32_e32 v10, v207
	v_mov_b32_e32 v11, v208
	v_mov_b32_e32 v8, v209
	v_mov_b32_e32 v9, v210
	v_mov_b32_e32 v6, v211
	v_mov_b32_e32 v7, v212
	ds_read_b128 v[24:27], v136 offset:512
	v_exp_f32_e32 v4, v29
	v_exp_f32_e32 v5, v28
	s_waitcnt vmcnt(31) lgkmcnt(1)
	v_fma_f32 v59, v19, v20, 0
	s_waitcnt vmcnt(30)
	v_fmac_f32_e32 v59, v32, v21
	s_waitcnt lgkmcnt(0)
	v_mul_f32_e32 v20, v24, v4
	v_mul_f32_e32 v20, v3, v20
	v_fmac_f32_e32 v20, v19, v5
	v_mul_f32_e32 v19, v25, v4
	v_mul_f32_e32 v19, v3, v19
	v_fmac_f32_e32 v19, v32, v5
	global_store_dword v140, v19, s[20:21]
	v_mul_f32_e32 v19, v26, v4
	v_mul_f32_e32 v19, v3, v19
	s_waitcnt vmcnt(30)
	v_fmac_f32_e32 v19, v33, v5
	global_store_dword v141, v19, s[20:21]
	v_mul_f32_e32 v19, v27, v4
	v_mul_f32_e32 v19, v3, v19
	v_fmac_f32_e32 v59, v33, v22
	s_waitcnt vmcnt(30)
	v_fmac_f32_e32 v19, v34, v5
	ds_read_b128 v[28:31], v136 offset:112
	global_store_dword v139, v20, s[20:21]
	v_fmac_f32_e32 v59, v34, v23
	ds_read_b128 v[20:23], v136 offset:16
	global_store_dword v142, v19, s[20:21]
	ds_read_b128 v[24:27], v136 offset:528
	ds_read_b128 v[32:35], v136 offset:32
	ds_read_b128 v[36:39], v136 offset:48
	ds_read_b128 v[40:43], v136 offset:544
	s_waitcnt lgkmcnt(3)
	v_mul_f32_e32 v19, v24, v4
	s_waitcnt vmcnt(31)
	v_fmac_f32_e32 v59, v44, v20
	v_mul_f32_e32 v19, v3, v19
	v_fmac_f32_e32 v19, v44, v5
	s_waitcnt vmcnt(30)
	v_fmac_f32_e32 v59, v45, v21
	global_store_dword v143, v19, s[20:21]
	v_mul_f32_e32 v19, v25, v4
	s_waitcnt vmcnt(30)
	v_fmac_f32_e32 v59, v46, v22
	v_mul_f32_e32 v19, v3, v19
	s_waitcnt vmcnt(29)
	v_fmac_f32_e32 v59, v47, v23
	v_fmac_f32_e32 v19, v45, v5
	s_waitcnt vmcnt(28) lgkmcnt(2)
	v_fmac_f32_e32 v59, v48, v32
	global_store_dword v144, v19, s[20:21]
	v_mul_f32_e32 v19, v26, v4
	v_mul_f32_e32 v19, v3, v19
	v_fmac_f32_e32 v19, v46, v5
	global_store_dword v145, v19, s[20:21]
	v_mul_f32_e32 v19, v27, v4
	v_mul_f32_e32 v19, v3, v19
	v_fmac_f32_e32 v19, v47, v5
	global_store_dword v146, v19, s[20:21]
	ds_read_b128 v[20:23], v136 offset:560
	ds_read_b128 v[24:27], v136 offset:64
	s_waitcnt vmcnt(30)
	v_fmac_f32_e32 v59, v49, v33
	s_waitcnt vmcnt(29)
	v_fmac_f32_e32 v59, v50, v34
	s_waitcnt vmcnt(28)
	v_fmac_f32_e32 v59, v51, v35
	ds_read_b128 v[32:35], v136 offset:576
	s_waitcnt vmcnt(19) lgkmcnt(4)
	v_fmac_f32_e32 v59, v2, v36
	s_waitcnt vmcnt(18)
	v_fmac_f32_e32 v59, v56, v37
	s_waitcnt vmcnt(17)
	v_fmac_f32_e32 v59, v57, v38
	s_waitcnt vmcnt(16)
	v_fmac_f32_e32 v59, v58, v39
	ds_read_b128 v[36:39], v136 offset:96
	s_waitcnt lgkmcnt(4)
	v_mul_f32_e32 v19, v40, v4
	v_mul_f32_e32 v19, v3, v19
	v_fmac_f32_e32 v19, v48, v5
	global_store_dword v147, v19, s[20:21]
	v_mul_f32_e32 v19, v41, v4
	v_mul_f32_e32 v19, v3, v19
	v_fmac_f32_e32 v19, v49, v5
	global_store_dword v148, v19, s[20:21]
	v_mul_f32_e32 v19, v42, v4
	v_mul_f32_e32 v19, v3, v19
	v_fmac_f32_e32 v19, v50, v5
	global_store_dword v149, v19, s[20:21]
	v_mul_f32_e32 v19, v4, v43
	v_mul_f32_e32 v19, v3, v19
	v_fmac_f32_e32 v19, v51, v5
	global_store_dword v150, v19, s[20:21]
	s_waitcnt lgkmcnt(3)
	v_mul_f32_e32 v19, v4, v20
	v_mul_f32_e32 v19, v3, v19
	v_fmac_f32_e32 v19, v2, v5
	v_mul_f32_e32 v2, v4, v21
	v_mul_f32_e32 v2, v3, v2
	v_fmac_f32_e32 v2, v56, v5
	global_store_dword v152, v2, s[20:21]
	v_mul_f32_e32 v2, v4, v22
	v_mul_f32_e32 v2, v3, v2
	v_fmac_f32_e32 v2, v57, v5
	global_store_dword v153, v2, s[20:21]
	v_mul_f32_e32 v2, v4, v23
	v_mul_f32_e32 v2, v3, v2
	v_fmac_f32_e32 v2, v58, v5
	global_store_dword v154, v2, s[20:21]
	s_waitcnt lgkmcnt(1)
; DI void smlstm_unit(const Args& a, LAS unsigned char* lds, int s, int h) {
;     ...
;       for (int i = 0; i < 32; ++i) { const int dk = part * 32 + i; num += QF[dk] * c0v[i]; Co[(size_t)dk * 128 + dv] = w_in * c0v[i] + wi * KF[dk] * vv; } }
;     RED[part * 128 + dv] = num;
;     __syncthreads();
;     if (tid < 128) { const float nt = (RED[dv] + RED[128 + dv]) + (RED[256 + dv] + RED[384 + dv]); const float sw = SCL[0] * wi; const float den = w_in * SCL[1] + sw;
;         HV[dv] = (w_in * nt + sw * vv) / fmaxf(fabsf(den), __expf(-mt));
;         a.out[O_NS + sh * 128 + dv] = w_in * n0[dv] + wi * KF[dv];
;         if (tid == 0) a.out[O_MS + sh] = mt; }
	v_mul_f32_e32 v2, v4, v32
	v_mul_f32_e32 v2, v3, v2
	v_fmac_f32_e32 v2, v52, v5
	global_store_dword v155, v2, s[20:21]
	v_mul_f32_e32 v2, v4, v33
	ds_read_b128 v[20:23], v136 offset:80
	v_fmac_f32_e32 v59, v52, v24
	v_mul_f32_e32 v2, v3, v2
	v_fmac_f32_e32 v59, v53, v25
	v_fmac_f32_e32 v2, v53, v5
	global_store_dword v156, v2, s[20:21]
	v_fmac_f32_e32 v59, v54, v26
	v_mul_f32_e32 v2, v4, v34
	v_mul_f32_e32 v2, v3, v2
	v_fmac_f32_e32 v59, v55, v27
	ds_read_b128 v[24:27], v136 offset:592
	v_fmac_f32_e32 v2, v54, v5
	global_store_dword v157, v2, s[20:21]
	v_mul_f32_e32 v2, v4, v35
	v_mul_f32_e32 v2, v3, v2
	v_fmac_f32_e32 v2, v55, v5
	global_store_dword v160, v2, s[20:21]
	ds_read_b128 v[32:35], v136 offset:608
	s_waitcnt lgkmcnt(1)
	v_mul_f32_e32 v2, v4, v24
	v_mul_f32_e32 v2, v3, v2
	v_fmac_f32_e32 v2, v16, v5
	v_pk_mul_f32 v[20:21], v[16:17], v[20:21]
	v_mul_f32_e32 v16, v4, v25
	v_mul_f32_e32 v16, v3, v16
	v_fmac_f32_e32 v16, v17, v5
	global_store_dword v162, v16, s[20:21]
	v_mul_f32_e32 v16, v4, v26
	v_mul_f32_e32 v16, v3, v16
	v_fmac_f32_e32 v16, v14, v5
	global_store_dword v163, v16, s[20:21]
	v_pk_mul_f32 v[16:17], v[14:15], v[22:23]
	v_mul_f32_e32 v14, v4, v27
	v_mul_f32_e32 v14, v3, v14
	v_fmac_f32_e32 v14, v15, v5
	global_store_dword v164, v14, s[20:21]
	s_waitcnt lgkmcnt(0)
	v_mul_f32_e32 v14, v4, v32
	v_mul_f32_e32 v14, v3, v14
	s_waitcnt vmcnt(29)
	v_fmac_f32_e32 v14, v12, v5
	global_store_dword v165, v14, s[20:21]
	s_waitcnt vmcnt(29)
	v_pk_mul_f32 v[14:15], v[12:13], v[36:37]
	v_mul_f32_e32 v12, v4, v33
	global_store_dword v161, v2, s[20:21]
	v_add_f32_e32 v2, v59, v20
	v_mul_f32_e32 v12, v3, v12
	v_add_f32_e32 v2, v2, v21
	v_fmac_f32_e32 v12, v13, v5
	v_add_f32_e32 v2, v2, v16
	global_store_dword v166, v12, s[20:21]
	v_mul_f32_e32 v12, v4, v34
	v_add_f32_e32 v2, v2, v17
	v_mul_f32_e32 v12, v3, v12
	v_add_f32_e32 v2, v2, v14
	s_waitcnt vmcnt(30)
	v_fmac_f32_e32 v12, v10, v5
	v_add_f32_e32 v2, v2, v15
	global_store_dword v167, v12, s[20:21]
	s_waitcnt vmcnt(30)
	v_pk_mul_f32 v[12:13], v[10:11], v[38:39]
	v_mul_f32_e32 v10, v4, v35
	v_add_f32_e32 v2, v2, v12
	v_add_f32_e32 v2, v2, v13
	ds_read_b128 v[12:15], v136 offset:624
	v_mul_f32_e32 v10, v3, v10
	v_fmac_f32_e32 v10, v11, v5
	global_store_dword v168, v10, s[20:21]
	global_store_dword v151, v19, s[20:21]
	s_waitcnt lgkmcnt(0)
	v_mul_f32_e32 v10, v4, v12
	v_mul_f32_e32 v10, v3, v10
	s_waitcnt vmcnt(31)
	v_fmac_f32_e32 v10, v8, v5
	global_store_dword v169, v10, s[20:21]
	s_waitcnt vmcnt(31)
	v_pk_mul_f32 v[10:11], v[8:9], v[28:29]
	v_mul_f32_e32 v8, v4, v13
	v_mul_f32_e32 v8, v3, v8
	v_fmac_f32_e32 v8, v9, v5
	global_store_dword v170, v8, s[20:21]
	v_mul_f32_e32 v8, v4, v14
	v_mul_f32_e32 v8, v3, v8
	v_add_f32_e32 v2, v2, v10
	s_waitcnt vmcnt(31)
	v_fmac_f32_e32 v8, v6, v5
	v_add_f32_e32 v2, v2, v11
	global_store_dword v171, v8, s[20:21]
	s_waitcnt vmcnt(31)
	v_pk_mul_f32 v[8:9], v[6:7], v[30:31]
	v_mul_f32_e32 v6, v4, v15
	v_add_f32_e32 v2, v2, v8
	v_mul_f32_e32 v6, v3, v6
	v_add_f32_e32 v2, v2, v9
	v_fmac_f32_e32 v6, v7, v5
	global_store_dword v172, v6, s[20:21]
	ds_write_b32 v218, v2 offset:1536
	s_waitcnt lgkmcnt(0)
	s_barrier
	s_and_saveexec_b64 s[20:21], s[2:3]
	s_cbranch_execz .LBB0_2134
	v_lshlrev_b32_e32 v132, 2, v130
	global_load_dword v6, v132, s[18:19]
	ds_read2st64_b32 v[8:9], v131 offset0:2 offset1:6
	ds_read2st64_b32 v[10:11], v218 offset0:8 offset1:10
	ds_read_b32 v13, v218 offset:3072
	ds_read_b64 v[14:15], v133 offset:4096
	v_mul_f32_e32 v7, 0xbfb8aa3b, v18
	s_waitcnt lgkmcnt(3)
	v_mov_b32_e32 v12, v9
	v_exp_f32_e32 v7, v7
	s_waitcnt lgkmcnt(1)
	v_pk_add_f32 v[10:11], v[10:11], v[12:13]
	v_mov_b32_e32 v2, v5
	v_mov_b32_e32 v16, v5
	v_mov_b32_e32 v17, v4
	s_waitcnt lgkmcnt(0)
	v_pk_mul_f32 v[4:5], v[4:5], v[14:15]
	v_pk_add_f32 v[10:11], v[10:11], v[10:11] op_sel:[0,1] op_sel_hi:[1,0]
	v_add_f32_e32 v5, v4, v5
	v_mov_b32_e32 v11, v4
	v_pk_mul_f32 v[2:3], v[2:3], v[10:11]
	v_max_f32_e64 v5, |v5|, v7
	v_add_f32_e32 v3, v2, v3
	v_div_scale_f32 v2, s[18:19], v5, v5, v3
	v_rcp_f32_e32 v4, v2
	v_mov_b32_e32 v7, v8
	v_div_scale_f32 v8, vcc, v3, v5, v3
	v_fma_f32 v9, -v2, v4, 1.0
	v_fmac_f32_e32 v4, v9, v4
	v_readlane_b32 s44, v253, 0
	v_mul_f32_e32 v9, v8, v4
	v_readlane_b32 s46, v253, 2
	v_fma_f32 v10, -v2, v9, v8
	v_readlane_b32 s47, v253, 3
	s_add_u32 s16, s46, s16
	v_fmac_f32_e32 v9, v10, v4
	s_addc_u32 s17, s47, s17
	v_fma_f32 v2, -v2, v9, v8
	v_lshl_add_u64 v[20:21], s[16:17], 0, v[132:133]
	v_div_fmas_f32 v4, v2, v4, v9
	v_add_co_u32_e32 v2, vcc, 0x7e34000, v20
	v_div_fixup_f32 v3, v4, v5, v3
	v_readlane_b32 s18, v254, 43
	ds_write_b32 v131, v3 offset:3584
	v_addc_co_u32_e32 v3, vcc, 0, v21, vcc
	v_readlane_b32 s19, v254, 44
	v_readlane_b32 s45, v253, 1
	s_waitcnt vmcnt(0)
	v_pk_mul_f32 v[4:5], v[16:17], v[6:7]
	s_nop 0
	v_add_f32_e32 v4, v4, v5
	global_store_dword v[2:3], v4, off offset:128
	s_and_b64 exec, exec, s[18:19]
	s_cbranch_execz .LBB0_2134
	s_mul_hi_i32 s9, s8, 0xfffffe04
	s_mulk_i32 s8, 0xfe04
	s_add_u32 s8, s16, s8
	s_addc_u32 s9, s17, s9
	global_store_dword v173, v18, s[8:9] offset:128
